# P0 S5 tables (critical path of phase 0): K-table loop rewritten by hand on all 512 threads, packed-f32 recurrence, halves combined through LDS
# speedup vs baseline: 1.0104x; 1.0104x over previous
.LBB0_92:
	ds_read2st64_b32 v[16:17], v3 offset1:17
	v_add_u32_e32 v14, 0x200, v14
	s_movk_i32 s4, 0x23f
	v_cmp_lt_u32_e64 s[4:5], s4, v14
	v_add_co_u32_e32 v18, vcc, 0x1000, v12
	s_or_b64 s[6:7], s[4:5], s[6:7]
	s_mov_b64 s[4:5], 0x800
	v_add_u32_e32 v3, 0x800, v3
	v_addc_co_u32_e32 v19, vcc, 0, v13, vcc
	s_waitcnt lgkmcnt(0)
	global_store_dword v[12:13], v16, off
	global_store_dword v[18:19], v17, off offset:256
	v_lshl_add_u64 v[12:13], v[12:13], 0, s[4:5]
	s_andn2_b64 exec, exec, s[6:7]
	s_cbranch_execnz .LBB0_92
	s_or_b64 exec, exec, s[6:7]
	v_and_b32_e32 v43, 0xff, v136
	v_lshrrev_b32_e32 v3, 4, v43
	v_and_b32_e32 v28, 15, v43
	v_lshrrev_b32_e32 v43, 8, v136
	v_lshlrev_b32_e32 v42, 7, v43
	v_lshl_add_u32 v29, v3, 8, v42
	v_add_u32_e32 v29, 0x4200, v29
	v_lshlrev_b32_e32 v31, 11, v43
	v_lshl_add_u32 v31, v28, 2, v31
	v_add_u32_e32 v31, 0x2200, v31
	v_mov_b32_e32 v26, 0
	v_mov_b32_e32 v27, 0
	v_mov_b32_e32 v24, 0
	v_mov_b32_e32 v25, 0
	v_mov_b32_e32 v22, 0
	v_mov_b32_e32 v23, 0
	v_mov_b32_e32 v20, 0
	v_mov_b32_e32 v21, 0
	v_mov_b32_e32 v18, 0
	v_mov_b32_e32 v19, 0
	v_mov_b32_e32 v16, 0
	v_mov_b32_e32 v17, 0
	v_mov_b32_e32 v14, 0
	v_mov_b32_e32 v15, 0
	v_mov_b32_e32 v12, 0
	v_mov_b32_e32 v13, 0
	s_mov_b32 s6, 0
.Lkt_loop:
	ds_read2st64_b32 v[38:39], v29 offset1:16
	ds_read2st64_b32 v[40:41], v31 offset1:16
	ds_read2st64_b32 v[36:37], v42 offset0:1 offset1:18
	s_waitcnt lgkmcnt(1)
	v_pk_mul_f32 v[34:35], v[38:39], v[40:41] op_sel:[1,1] op_sel_hi:[1,0]
	v_pk_fma_f32 v[32:33], v[38:39], v[40:41], v[34:35] op_sel_hi:[0,1,1] neg_lo:[0,0,1]
	s_waitcnt lgkmcnt(0)
	v_add_f32_e32 v26, v26, v32
	v_pk_mul_f32 v[34:35], v[32:33], v[36:37] op_sel:[1,1] op_sel_hi:[1,0]
	v_pk_fma_f32 v[32:33], v[32:33], v[36:37], v[34:35] op_sel_hi:[0,1,1] neg_lo:[0,0,1]
	v_add_f32_e32 v27, v27, v32
	v_pk_mul_f32 v[34:35], v[32:33], v[36:37] op_sel:[1,1] op_sel_hi:[1,0]
	v_pk_fma_f32 v[32:33], v[32:33], v[36:37], v[34:35] op_sel_hi:[0,1,1] neg_lo:[0,0,1]
	v_add_f32_e32 v24, v24, v32
	v_pk_mul_f32 v[34:35], v[32:33], v[36:37] op_sel:[1,1] op_sel_hi:[1,0]
	v_pk_fma_f32 v[32:33], v[32:33], v[36:37], v[34:35] op_sel_hi:[0,1,1] neg_lo:[0,0,1]
	v_add_f32_e32 v25, v25, v32
	v_pk_mul_f32 v[34:35], v[32:33], v[36:37] op_sel:[1,1] op_sel_hi:[1,0]
	v_pk_fma_f32 v[32:33], v[32:33], v[36:37], v[34:35] op_sel_hi:[0,1,1] neg_lo:[0,0,1]
	v_add_f32_e32 v22, v22, v32
	v_pk_mul_f32 v[34:35], v[32:33], v[36:37] op_sel:[1,1] op_sel_hi:[1,0]
	v_pk_fma_f32 v[32:33], v[32:33], v[36:37], v[34:35] op_sel_hi:[0,1,1] neg_lo:[0,0,1]
	v_add_f32_e32 v23, v23, v32
	v_pk_mul_f32 v[34:35], v[32:33], v[36:37] op_sel:[1,1] op_sel_hi:[1,0]
	v_pk_fma_f32 v[32:33], v[32:33], v[36:37], v[34:35] op_sel_hi:[0,1,1] neg_lo:[0,0,1]
	v_add_f32_e32 v20, v20, v32
	v_pk_mul_f32 v[34:35], v[32:33], v[36:37] op_sel:[1,1] op_sel_hi:[1,0]
	v_pk_fma_f32 v[32:33], v[32:33], v[36:37], v[34:35] op_sel_hi:[0,1,1] neg_lo:[0,0,1]
	v_add_f32_e32 v21, v21, v32
	v_pk_mul_f32 v[34:35], v[32:33], v[36:37] op_sel:[1,1] op_sel_hi:[1,0]
	v_pk_fma_f32 v[32:33], v[32:33], v[36:37], v[34:35] op_sel_hi:[0,1,1] neg_lo:[0,0,1]
	v_add_f32_e32 v18, v18, v32
	v_pk_mul_f32 v[34:35], v[32:33], v[36:37] op_sel:[1,1] op_sel_hi:[1,0]
	v_pk_fma_f32 v[32:33], v[32:33], v[36:37], v[34:35] op_sel_hi:[0,1,1] neg_lo:[0,0,1]
	v_add_f32_e32 v19, v19, v32
	v_pk_mul_f32 v[34:35], v[32:33], v[36:37] op_sel:[1,1] op_sel_hi:[1,0]
	v_pk_fma_f32 v[32:33], v[32:33], v[36:37], v[34:35] op_sel_hi:[0,1,1] neg_lo:[0,0,1]
	v_add_f32_e32 v16, v16, v32
	v_pk_mul_f32 v[34:35], v[32:33], v[36:37] op_sel:[1,1] op_sel_hi:[1,0]
	v_pk_fma_f32 v[32:33], v[32:33], v[36:37], v[34:35] op_sel_hi:[0,1,1] neg_lo:[0,0,1]
	v_add_f32_e32 v17, v17, v32
	v_pk_mul_f32 v[34:35], v[32:33], v[36:37] op_sel:[1,1] op_sel_hi:[1,0]
	v_pk_fma_f32 v[32:33], v[32:33], v[36:37], v[34:35] op_sel_hi:[0,1,1] neg_lo:[0,0,1]
	v_add_f32_e32 v14, v14, v32
	v_pk_mul_f32 v[34:35], v[32:33], v[36:37] op_sel:[1,1] op_sel_hi:[1,0]
	v_pk_fma_f32 v[32:33], v[32:33], v[36:37], v[34:35] op_sel_hi:[0,1,1] neg_lo:[0,0,1]
	v_add_f32_e32 v15, v15, v32
	v_pk_mul_f32 v[34:35], v[32:33], v[36:37] op_sel:[1,1] op_sel_hi:[1,0]
	v_pk_fma_f32 v[32:33], v[32:33], v[36:37], v[34:35] op_sel_hi:[0,1,1] neg_lo:[0,0,1]
	v_add_f32_e32 v12, v12, v32
	v_pk_mul_f32 v[34:35], v[32:33], v[36:37] op_sel:[1,1] op_sel_hi:[1,0]
	v_pk_fma_f32 v[32:33], v[32:33], v[36:37], v[34:35] op_sel_hi:[0,1,1] neg_lo:[0,0,1]
	v_add_f32_e32 v13, v13, v32
	v_add_u32_e32 v29, 4, v29
	v_add_u32_e32 v31, 64, v31
	v_add_u32_e32 v42, 4, v42
	s_add_i32 s6, s6, 1
	s_cmp_lt_u32 s6, 32
	s_cbranch_scc1 .Lkt_loop
	v_and_b32_e32 v29, 0xff, v136
	v_lshlrev_b32_e32 v29, 2, v29
	v_add_u32_e32 v29, 0x10000, v29
	s_movk_i32 s4, 0xff
	v_cmp_lt_u32_e32 vcc, s4, v136
	s_and_saveexec_b64 s[4:5], vcc
	ds_write_b32 v29, v26
	ds_write_b32 v29, v27 offset:1024
	ds_write_b32 v29, v24 offset:2048
	ds_write_b32 v29, v25 offset:3072
	ds_write_b32 v29, v22 offset:4096
	ds_write_b32 v29, v23 offset:5120
	ds_write_b32 v29, v20 offset:6144
	ds_write_b32 v29, v21 offset:7168
	ds_write_b32 v29, v18 offset:8192
	ds_write_b32 v29, v19 offset:9216
	ds_write_b32 v29, v16 offset:10240
	ds_write_b32 v29, v17 offset:11264
	ds_write_b32 v29, v14 offset:12288
	ds_write_b32 v29, v15 offset:13312
	ds_write_b32 v29, v12 offset:14336
	ds_write_b32 v29, v13 offset:15360
	s_or_b64 exec, exec, s[4:5]
	s_waitcnt lgkmcnt(0)
	s_barrier
	s_movk_i32 s4, 0x100
	v_cmp_gt_u32_e32 vcc, s4, v136
	s_and_saveexec_b64 s[4:5], vcc
	s_cbranch_execz .LBB0_99
	ds_read_b32 v32, v29
	ds_read_b32 v33, v29 offset:1024
	ds_read_b32 v34, v29 offset:2048
	ds_read_b32 v35, v29 offset:3072
	ds_read_b32 v36, v29 offset:4096
	ds_read_b32 v37, v29 offset:5120
	ds_read_b32 v38, v29 offset:6144
	ds_read_b32 v39, v29 offset:7168
	s_waitcnt lgkmcnt(0)
	v_add_f32_e32 v26, v26, v32
	v_add_f32_e32 v27, v27, v33
	v_add_f32_e32 v24, v24, v34
	v_add_f32_e32 v25, v25, v35
	v_add_f32_e32 v22, v22, v36
	v_add_f32_e32 v23, v23, v37
	v_add_f32_e32 v20, v20, v38
	v_add_f32_e32 v21, v21, v39
	ds_read_b32 v32, v29 offset:8192
	ds_read_b32 v33, v29 offset:9216
	ds_read_b32 v34, v29 offset:10240
	ds_read_b32 v35, v29 offset:11264
	ds_read_b32 v36, v29 offset:12288
	ds_read_b32 v37, v29 offset:13312
	ds_read_b32 v38, v29 offset:14336
	ds_read_b32 v39, v29 offset:15360
	s_waitcnt lgkmcnt(0)
	v_add_f32_e32 v18, v18, v32
	v_add_f32_e32 v19, v19, v33
	v_add_f32_e32 v16, v16, v34
	v_add_f32_e32 v17, v17, v35
	v_add_f32_e32 v14, v14, v36
	v_add_f32_e32 v15, v15, v37
	v_add_f32_e32 v12, v12, v38
	v_add_f32_e32 v13, v13, v39
	v_cmp_eq_u32_e32 vcc, v3, v28
	v_mov_b32_e32 v29, 0
	v_mov_b32_e32 v31, 0
	s_and_saveexec_b64 s[6:7], vcc
	s_cbranch_execz .LBB0_98
	s_load_dwordx16 s[12:27], s[0:1], 0x80
	v_lshl_or_b32 v32, s2, 4, v3
	v_mov_b32_e32 v33, 0
	s_waitcnt lgkmcnt(0)
	v_lshl_add_u64 v[32:33], v[32:33], 2, s[24:25]
	global_load_dword v31, v[32:33], off
